# v121 stack plus straight-line MOD SiLU fill (33 loads in flight instead of 36 serialized load-wait-SiLU trips per k-chunk)
# speedup vs baseline: 1.0048x; 1.0048x over previous
.LBB0_1319:
	v_lshl_or_b32 v176, s31, 8, v102
	v_lshl_add_u64 v[0:1], v[176:177], 2, s[78:79]
	s_mov_b32 s58, 0
	s_waitcnt vmcnt(0)
	v_mov_b32_e32 v2, v69
	s_waitcnt vmcnt(63) expcnt(7) lgkmcnt(15)
	s_barrier
	v_lshlrev_b32_e32 v128, 2, v176
	s_mov_b64 s[100:101], s[74:75]
	global_load_dword v129, v128, s[100:101]
	s_add_u32 s100, s100, 0x1000
	s_addc_u32 s101, s101, 0
	global_load_dword v130, v128, s[100:101]
	s_add_u32 s100, s100, 0x1000
	s_addc_u32 s101, s101, 0
	global_load_dword v131, v128, s[100:101]
	s_add_u32 s100, s100, 0x1000
	s_addc_u32 s101, s101, 0
	global_load_dword v132, v128, s[100:101]
	s_add_u32 s100, s100, 0x1000
	s_addc_u32 s101, s101, 0
	global_load_dword v133, v128, s[100:101]
	s_add_u32 s100, s100, 0x1000
	s_addc_u32 s101, s101, 0
	global_load_dword v134, v128, s[100:101]
	s_add_u32 s100, s100, 0x1000
	s_addc_u32 s101, s101, 0
	global_load_dword v135, v128, s[100:101]
	s_add_u32 s100, s100, 0x1000
	s_addc_u32 s101, s101, 0
	global_load_dword v136, v128, s[100:101]
	s_add_u32 s100, s100, 0x1000
	s_addc_u32 s101, s101, 0
	global_load_dword v137, v128, s[100:101]
	s_add_u32 s100, s100, 0x1000
	s_addc_u32 s101, s101, 0
	global_load_dword v138, v128, s[100:101]
	s_add_u32 s100, s100, 0x1000
	s_addc_u32 s101, s101, 0
	global_load_dword v139, v128, s[100:101]
	s_add_u32 s100, s100, 0x1000
	s_addc_u32 s101, s101, 0
	global_load_dword v140, v128, s[100:101]
	s_add_u32 s100, s100, 0x1000
	s_addc_u32 s101, s101, 0
	global_load_dword v141, v128, s[100:101]
	s_add_u32 s100, s100, 0x1000
	s_addc_u32 s101, s101, 0
	global_load_dword v142, v128, s[100:101]
	s_add_u32 s100, s100, 0x1000
	s_addc_u32 s101, s101, 0
	global_load_dword v143, v128, s[100:101]
	s_add_u32 s100, s100, 0x1000
	s_addc_u32 s101, s101, 0
	global_load_dword v144, v128, s[100:101]
	s_add_u32 s100, s100, 0x1000
	s_addc_u32 s101, s101, 0
	global_load_dword v145, v128, s[100:101]
	s_add_u32 s100, s100, 0x1000
	s_addc_u32 s101, s101, 0
	global_load_dword v146, v128, s[100:101]
	s_add_u32 s100, s100, 0x1000
	s_addc_u32 s101, s101, 0
	global_load_dword v147, v128, s[100:101]
	s_add_u32 s100, s100, 0x1000
	s_addc_u32 s101, s101, 0
	global_load_dword v148, v128, s[100:101]
	s_add_u32 s100, s100, 0x1000
	s_addc_u32 s101, s101, 0
	global_load_dword v149, v128, s[100:101]
	s_add_u32 s100, s100, 0x1000
	s_addc_u32 s101, s101, 0
	global_load_dword v150, v128, s[100:101]
	s_add_u32 s100, s100, 0x1000
	s_addc_u32 s101, s101, 0
	global_load_dword v151, v128, s[100:101]
	s_add_u32 s100, s100, 0x1000
	s_addc_u32 s101, s101, 0
	global_load_dword v152, v128, s[100:101]
	s_add_u32 s100, s100, 0x1000
	s_addc_u32 s101, s101, 0
	global_load_dword v153, v128, s[100:101]
	s_add_u32 s100, s100, 0x1000
	s_addc_u32 s101, s101, 0
	global_load_dword v154, v128, s[100:101]
	s_add_u32 s100, s100, 0x1000
	s_addc_u32 s101, s101, 0
	global_load_dword v155, v128, s[100:101]
	s_add_u32 s100, s100, 0x1000
	s_addc_u32 s101, s101, 0
	global_load_dword v156, v128, s[100:101]
	s_add_u32 s100, s100, 0x1000
	s_addc_u32 s101, s101, 0
	global_load_dword v157, v128, s[100:101]
	s_add_u32 s100, s100, 0x1000
	s_addc_u32 s101, s101, 0
	global_load_dword v158, v128, s[100:101]
	s_add_u32 s100, s100, 0x1000
	s_addc_u32 s101, s101, 0
	global_load_dword v159, v128, s[100:101]
	s_add_u32 s100, s100, 0x1000
	s_addc_u32 s101, s101, 0
	global_load_dword v160, v128, s[100:101]
	global_load_dword v161, v[0:1], off
	v_mov_b32_e32 v162, 0
	ds_write_b32 v104, v162 offset:33792
	ds_write_b32 v104, v162 offset:34816
	ds_write_b32 v104, v162 offset:35840
	s_waitcnt vmcnt(32)
	v_mul_f32_e32 v163, 0xbfb8aa3b, v129
	v_exp_f32_e32 v163, v163
	s_nop 0
	v_add_f32_e32 v163, 1.0, v163
	v_div_scale_f32 v164, s[0:1], v163, v163, v129
	v_rcp_f32_e32 v165, v164
	v_div_scale_f32 v166, vcc, v129, v163, v129
	v_fma_f32 v167, -v164, v165, 1.0
	v_fmac_f32_e32 v165, v167, v165
	v_mul_f32_e32 v167, v166, v165
	v_fma_f32 v168, -v164, v167, v166
	v_fmac_f32_e32 v167, v168, v165
	v_fma_f32 v164, -v164, v167, v166
	v_div_fmas_f32 v164, v164, v165, v167
	v_div_fixup_f32 v129, v164, v163, v129
	ds_write_b32 v104, v129 offset:0
	s_waitcnt vmcnt(31)
	v_mul_f32_e32 v163, 0xbfb8aa3b, v130
	v_exp_f32_e32 v163, v163
	s_nop 0
	v_add_f32_e32 v163, 1.0, v163
	v_div_scale_f32 v164, s[0:1], v163, v163, v130
	v_rcp_f32_e32 v165, v164
	v_div_scale_f32 v166, vcc, v130, v163, v130
	v_fma_f32 v167, -v164, v165, 1.0
	v_fmac_f32_e32 v165, v167, v165
	v_mul_f32_e32 v167, v166, v165
	v_fma_f32 v168, -v164, v167, v166
	v_fmac_f32_e32 v167, v168, v165
	v_fma_f32 v164, -v164, v167, v166
	v_div_fmas_f32 v164, v164, v165, v167
	v_div_fixup_f32 v130, v164, v163, v130
	ds_write_b32 v104, v130 offset:1024
	s_waitcnt vmcnt(30)
	v_mul_f32_e32 v163, 0xbfb8aa3b, v131
	v_exp_f32_e32 v163, v163
	s_nop 0
	v_add_f32_e32 v163, 1.0, v163
	v_div_scale_f32 v164, s[0:1], v163, v163, v131
	v_rcp_f32_e32 v165, v164
	v_div_scale_f32 v166, vcc, v131, v163, v131
	v_fma_f32 v167, -v164, v165, 1.0
	v_fmac_f32_e32 v165, v167, v165
	v_mul_f32_e32 v167, v166, v165
	v_fma_f32 v168, -v164, v167, v166
	v_fmac_f32_e32 v167, v168, v165
	v_fma_f32 v164, -v164, v167, v166
	v_div_fmas_f32 v164, v164, v165, v167
	v_div_fixup_f32 v131, v164, v163, v131
	ds_write_b32 v104, v131 offset:2048
	s_waitcnt vmcnt(29)
	v_mul_f32_e32 v163, 0xbfb8aa3b, v132
	v_exp_f32_e32 v163, v163
	s_nop 0
	v_add_f32_e32 v163, 1.0, v163
	v_div_scale_f32 v164, s[0:1], v163, v163, v132
	v_rcp_f32_e32 v165, v164
	v_div_scale_f32 v166, vcc, v132, v163, v132
	v_fma_f32 v167, -v164, v165, 1.0
	v_fmac_f32_e32 v165, v167, v165
	v_mul_f32_e32 v167, v166, v165
	v_fma_f32 v168, -v164, v167, v166
	v_fmac_f32_e32 v167, v168, v165
	v_fma_f32 v164, -v164, v167, v166
	v_div_fmas_f32 v164, v164, v165, v167
	v_div_fixup_f32 v132, v164, v163, v132
	ds_write_b32 v104, v132 offset:3072
	s_waitcnt vmcnt(28)
	v_mul_f32_e32 v163, 0xbfb8aa3b, v133
	v_exp_f32_e32 v163, v163
	s_nop 0
	v_add_f32_e32 v163, 1.0, v163
	v_div_scale_f32 v164, s[0:1], v163, v163, v133
	v_rcp_f32_e32 v165, v164
	v_div_scale_f32 v166, vcc, v133, v163, v133
	v_fma_f32 v167, -v164, v165, 1.0
	v_fmac_f32_e32 v165, v167, v165
	v_mul_f32_e32 v167, v166, v165
	v_fma_f32 v168, -v164, v167, v166
	v_fmac_f32_e32 v167, v168, v165
	v_fma_f32 v164, -v164, v167, v166
	v_div_fmas_f32 v164, v164, v165, v167
	v_div_fixup_f32 v133, v164, v163, v133
	ds_write_b32 v104, v133 offset:4096
	s_waitcnt vmcnt(27)
	v_mul_f32_e32 v163, 0xbfb8aa3b, v134
	v_exp_f32_e32 v163, v163
	s_nop 0
	v_add_f32_e32 v163, 1.0, v163
	v_div_scale_f32 v164, s[0:1], v163, v163, v134
	v_rcp_f32_e32 v165, v164
	v_div_scale_f32 v166, vcc, v134, v163, v134
	v_fma_f32 v167, -v164, v165, 1.0
	v_fmac_f32_e32 v165, v167, v165
	v_mul_f32_e32 v167, v166, v165
	v_fma_f32 v168, -v164, v167, v166
	v_fmac_f32_e32 v167, v168, v165
	v_fma_f32 v164, -v164, v167, v166
	v_div_fmas_f32 v164, v164, v165, v167
	v_div_fixup_f32 v134, v164, v163, v134
	ds_write_b32 v104, v134 offset:5120
	s_waitcnt vmcnt(26)
	v_mul_f32_e32 v163, 0xbfb8aa3b, v135
	v_exp_f32_e32 v163, v163
	s_nop 0
	v_add_f32_e32 v163, 1.0, v163
	v_div_scale_f32 v164, s[0:1], v163, v163, v135
	v_rcp_f32_e32 v165, v164
	v_div_scale_f32 v166, vcc, v135, v163, v135
	v_fma_f32 v167, -v164, v165, 1.0
	v_fmac_f32_e32 v165, v167, v165
	v_mul_f32_e32 v167, v166, v165
	v_fma_f32 v168, -v164, v167, v166
	v_fmac_f32_e32 v167, v168, v165
	v_fma_f32 v164, -v164, v167, v166
	v_div_fmas_f32 v164, v164, v165, v167
	v_div_fixup_f32 v135, v164, v163, v135
	ds_write_b32 v104, v135 offset:6144
	s_waitcnt vmcnt(25)
	v_mul_f32_e32 v163, 0xbfb8aa3b, v136
	v_exp_f32_e32 v163, v163
	s_nop 0
	v_add_f32_e32 v163, 1.0, v163
	v_div_scale_f32 v164, s[0:1], v163, v163, v136
	v_rcp_f32_e32 v165, v164
	v_div_scale_f32 v166, vcc, v136, v163, v136
	v_fma_f32 v167, -v164, v165, 1.0
	v_fmac_f32_e32 v165, v167, v165
	v_mul_f32_e32 v167, v166, v165
	v_fma_f32 v168, -v164, v167, v166
	v_fmac_f32_e32 v167, v168, v165
	v_fma_f32 v164, -v164, v167, v166
	v_div_fmas_f32 v164, v164, v165, v167
	v_div_fixup_f32 v136, v164, v163, v136
	ds_write_b32 v104, v136 offset:7168
	s_waitcnt vmcnt(24)
	v_mul_f32_e32 v163, 0xbfb8aa3b, v137
	v_exp_f32_e32 v163, v163
	s_nop 0
	v_add_f32_e32 v163, 1.0, v163
	v_div_scale_f32 v164, s[0:1], v163, v163, v137
	v_rcp_f32_e32 v165, v164
	v_div_scale_f32 v166, vcc, v137, v163, v137
	v_fma_f32 v167, -v164, v165, 1.0
	v_fmac_f32_e32 v165, v167, v165
	v_mul_f32_e32 v167, v166, v165
	v_fma_f32 v168, -v164, v167, v166
	v_fmac_f32_e32 v167, v168, v165
	v_fma_f32 v164, -v164, v167, v166
	v_div_fmas_f32 v164, v164, v165, v167
	v_div_fixup_f32 v137, v164, v163, v137
	ds_write_b32 v104, v137 offset:8192
	s_waitcnt vmcnt(23)
	v_mul_f32_e32 v163, 0xbfb8aa3b, v138
	v_exp_f32_e32 v163, v163
	s_nop 0
	v_add_f32_e32 v163, 1.0, v163
	v_div_scale_f32 v164, s[0:1], v163, v163, v138
	v_rcp_f32_e32 v165, v164
	v_div_scale_f32 v166, vcc, v138, v163, v138
	v_fma_f32 v167, -v164, v165, 1.0
	v_fmac_f32_e32 v165, v167, v165
	v_mul_f32_e32 v167, v166, v165
	v_fma_f32 v168, -v164, v167, v166
	v_fmac_f32_e32 v167, v168, v165
	v_fma_f32 v164, -v164, v167, v166
	v_div_fmas_f32 v164, v164, v165, v167
	v_div_fixup_f32 v138, v164, v163, v138
	ds_write_b32 v104, v138 offset:9216
	s_waitcnt vmcnt(22)
	v_mul_f32_e32 v163, 0xbfb8aa3b, v139
	v_exp_f32_e32 v163, v163
	s_nop 0
	v_add_f32_e32 v163, 1.0, v163
	v_div_scale_f32 v164, s[0:1], v163, v163, v139
	v_rcp_f32_e32 v165, v164
	v_div_scale_f32 v166, vcc, v139, v163, v139
	v_fma_f32 v167, -v164, v165, 1.0
	v_fmac_f32_e32 v165, v167, v165
	v_mul_f32_e32 v167, v166, v165
	v_fma_f32 v168, -v164, v167, v166
	v_fmac_f32_e32 v167, v168, v165
	v_fma_f32 v164, -v164, v167, v166
	v_div_fmas_f32 v164, v164, v165, v167
	v_div_fixup_f32 v139, v164, v163, v139
	ds_write_b32 v104, v139 offset:10240
	s_waitcnt vmcnt(21)
	v_mul_f32_e32 v163, 0xbfb8aa3b, v140
	v_exp_f32_e32 v163, v163
	s_nop 0
	v_add_f32_e32 v163, 1.0, v163
	v_div_scale_f32 v164, s[0:1], v163, v163, v140
	v_rcp_f32_e32 v165, v164
	v_div_scale_f32 v166, vcc, v140, v163, v140
	v_fma_f32 v167, -v164, v165, 1.0
	v_fmac_f32_e32 v165, v167, v165
	v_mul_f32_e32 v167, v166, v165
	v_fma_f32 v168, -v164, v167, v166
	v_fmac_f32_e32 v167, v168, v165
	v_fma_f32 v164, -v164, v167, v166
	v_div_fmas_f32 v164, v164, v165, v167
	v_div_fixup_f32 v140, v164, v163, v140
	ds_write_b32 v104, v140 offset:11264
	s_waitcnt vmcnt(20)
	v_mul_f32_e32 v163, 0xbfb8aa3b, v141
	v_exp_f32_e32 v163, v163
	s_nop 0
	v_add_f32_e32 v163, 1.0, v163
	v_div_scale_f32 v164, s[0:1], v163, v163, v141
	v_rcp_f32_e32 v165, v164
	v_div_scale_f32 v166, vcc, v141, v163, v141
	v_fma_f32 v167, -v164, v165, 1.0
	v_fmac_f32_e32 v165, v167, v165
	v_mul_f32_e32 v167, v166, v165
	v_fma_f32 v168, -v164, v167, v166
	v_fmac_f32_e32 v167, v168, v165
	v_fma_f32 v164, -v164, v167, v166
	v_div_fmas_f32 v164, v164, v165, v167
	v_div_fixup_f32 v141, v164, v163, v141
	ds_write_b32 v104, v141 offset:12288
	s_waitcnt vmcnt(19)
	v_mul_f32_e32 v163, 0xbfb8aa3b, v142
	v_exp_f32_e32 v163, v163
	s_nop 0
	v_add_f32_e32 v163, 1.0, v163
	v_div_scale_f32 v164, s[0:1], v163, v163, v142
	v_rcp_f32_e32 v165, v164
	v_div_scale_f32 v166, vcc, v142, v163, v142
	v_fma_f32 v167, -v164, v165, 1.0
	v_fmac_f32_e32 v165, v167, v165
	v_mul_f32_e32 v167, v166, v165
	v_fma_f32 v168, -v164, v167, v166
	v_fmac_f32_e32 v167, v168, v165
	v_fma_f32 v164, -v164, v167, v166
	v_div_fmas_f32 v164, v164, v165, v167
	v_div_fixup_f32 v142, v164, v163, v142
	ds_write_b32 v104, v142 offset:13312
	s_waitcnt vmcnt(18)
	v_mul_f32_e32 v163, 0xbfb8aa3b, v143
	v_exp_f32_e32 v163, v163
	s_nop 0
	v_add_f32_e32 v163, 1.0, v163
	v_div_scale_f32 v164, s[0:1], v163, v163, v143
	v_rcp_f32_e32 v165, v164
	v_div_scale_f32 v166, vcc, v143, v163, v143
	v_fma_f32 v167, -v164, v165, 1.0
	v_fmac_f32_e32 v165, v167, v165
	v_mul_f32_e32 v167, v166, v165
	v_fma_f32 v168, -v164, v167, v166
	v_fmac_f32_e32 v167, v168, v165
	v_fma_f32 v164, -v164, v167, v166
	v_div_fmas_f32 v164, v164, v165, v167
	v_div_fixup_f32 v143, v164, v163, v143
	ds_write_b32 v104, v143 offset:14336
	s_waitcnt vmcnt(17)
	v_mul_f32_e32 v163, 0xbfb8aa3b, v144
	v_exp_f32_e32 v163, v163
	s_nop 0
	v_add_f32_e32 v163, 1.0, v163
	v_div_scale_f32 v164, s[0:1], v163, v163, v144
	v_rcp_f32_e32 v165, v164
	v_div_scale_f32 v166, vcc, v144, v163, v144
	v_fma_f32 v167, -v164, v165, 1.0
	v_fmac_f32_e32 v165, v167, v165
	v_mul_f32_e32 v167, v166, v165
	v_fma_f32 v168, -v164, v167, v166
	v_fmac_f32_e32 v167, v168, v165
	v_fma_f32 v164, -v164, v167, v166
	v_div_fmas_f32 v164, v164, v165, v167
	v_div_fixup_f32 v144, v164, v163, v144
	ds_write_b32 v104, v144 offset:15360
	s_waitcnt vmcnt(16)
	v_mul_f32_e32 v163, 0xbfb8aa3b, v145
	v_exp_f32_e32 v163, v163
	s_nop 0
	v_add_f32_e32 v163, 1.0, v163
	v_div_scale_f32 v164, s[0:1], v163, v163, v145
	v_rcp_f32_e32 v165, v164
	v_div_scale_f32 v166, vcc, v145, v163, v145
	v_fma_f32 v167, -v164, v165, 1.0
	v_fmac_f32_e32 v165, v167, v165
	v_mul_f32_e32 v167, v166, v165
	v_fma_f32 v168, -v164, v167, v166
	v_fmac_f32_e32 v167, v168, v165
	v_fma_f32 v164, -v164, v167, v166
	v_div_fmas_f32 v164, v164, v165, v167
	v_div_fixup_f32 v145, v164, v163, v145
	ds_write_b32 v104, v145 offset:16384
	s_waitcnt vmcnt(15)
	v_mul_f32_e32 v163, 0xbfb8aa3b, v146
	v_exp_f32_e32 v163, v163
	s_nop 0
	v_add_f32_e32 v163, 1.0, v163
	v_div_scale_f32 v164, s[0:1], v163, v163, v146
	v_rcp_f32_e32 v165, v164
	v_div_scale_f32 v166, vcc, v146, v163, v146
	v_fma_f32 v167, -v164, v165, 1.0
	v_fmac_f32_e32 v165, v167, v165
	v_mul_f32_e32 v167, v166, v165
	v_fma_f32 v168, -v164, v167, v166
	v_fmac_f32_e32 v167, v168, v165
	v_fma_f32 v164, -v164, v167, v166
	v_div_fmas_f32 v164, v164, v165, v167
	v_div_fixup_f32 v146, v164, v163, v146
	ds_write_b32 v104, v146 offset:17408
	s_waitcnt vmcnt(14)
	v_mul_f32_e32 v163, 0xbfb8aa3b, v147
	v_exp_f32_e32 v163, v163
	s_nop 0
	v_add_f32_e32 v163, 1.0, v163
	v_div_scale_f32 v164, s[0:1], v163, v163, v147
	v_rcp_f32_e32 v165, v164
	v_div_scale_f32 v166, vcc, v147, v163, v147
	v_fma_f32 v167, -v164, v165, 1.0
	v_fmac_f32_e32 v165, v167, v165
	v_mul_f32_e32 v167, v166, v165
	v_fma_f32 v168, -v164, v167, v166
	v_fmac_f32_e32 v167, v168, v165
	v_fma_f32 v164, -v164, v167, v166
	v_div_fmas_f32 v164, v164, v165, v167
	v_div_fixup_f32 v147, v164, v163, v147
	ds_write_b32 v104, v147 offset:18432
	s_waitcnt vmcnt(13)
	v_mul_f32_e32 v163, 0xbfb8aa3b, v148
	v_exp_f32_e32 v163, v163
	s_nop 0
	v_add_f32_e32 v163, 1.0, v163
	v_div_scale_f32 v164, s[0:1], v163, v163, v148
	v_rcp_f32_e32 v165, v164
	v_div_scale_f32 v166, vcc, v148, v163, v148
	v_fma_f32 v167, -v164, v165, 1.0
	v_fmac_f32_e32 v165, v167, v165
	v_mul_f32_e32 v167, v166, v165
	v_fma_f32 v168, -v164, v167, v166
	v_fmac_f32_e32 v167, v168, v165
	v_fma_f32 v164, -v164, v167, v166
	v_div_fmas_f32 v164, v164, v165, v167
	v_div_fixup_f32 v148, v164, v163, v148
	ds_write_b32 v104, v148 offset:19456
	s_waitcnt vmcnt(12)
	v_mul_f32_e32 v163, 0xbfb8aa3b, v149
	v_exp_f32_e32 v163, v163
	s_nop 0
	v_add_f32_e32 v163, 1.0, v163
	v_div_scale_f32 v164, s[0:1], v163, v163, v149
	v_rcp_f32_e32 v165, v164
	v_div_scale_f32 v166, vcc, v149, v163, v149
	v_fma_f32 v167, -v164, v165, 1.0
	v_fmac_f32_e32 v165, v167, v165
	v_mul_f32_e32 v167, v166, v165
	v_fma_f32 v168, -v164, v167, v166
	v_fmac_f32_e32 v167, v168, v165
	v_fma_f32 v164, -v164, v167, v166
	v_div_fmas_f32 v164, v164, v165, v167
	v_div_fixup_f32 v149, v164, v163, v149
	ds_write_b32 v104, v149 offset:20480
	s_waitcnt vmcnt(11)
	v_mul_f32_e32 v163, 0xbfb8aa3b, v150
	v_exp_f32_e32 v163, v163
	s_nop 0
	v_add_f32_e32 v163, 1.0, v163
	v_div_scale_f32 v164, s[0:1], v163, v163, v150
	v_rcp_f32_e32 v165, v164
	v_div_scale_f32 v166, vcc, v150, v163, v150
	v_fma_f32 v167, -v164, v165, 1.0
	v_fmac_f32_e32 v165, v167, v165
	v_mul_f32_e32 v167, v166, v165
	v_fma_f32 v168, -v164, v167, v166
	v_fmac_f32_e32 v167, v168, v165
	v_fma_f32 v164, -v164, v167, v166
	v_div_fmas_f32 v164, v164, v165, v167
	v_div_fixup_f32 v150, v164, v163, v150
	ds_write_b32 v104, v150 offset:21504
	s_waitcnt vmcnt(10)
	v_mul_f32_e32 v163, 0xbfb8aa3b, v151
	v_exp_f32_e32 v163, v163
	s_nop 0
	v_add_f32_e32 v163, 1.0, v163
	v_div_scale_f32 v164, s[0:1], v163, v163, v151
	v_rcp_f32_e32 v165, v164
	v_div_scale_f32 v166, vcc, v151, v163, v151
	v_fma_f32 v167, -v164, v165, 1.0
	v_fmac_f32_e32 v165, v167, v165
	v_mul_f32_e32 v167, v166, v165
	v_fma_f32 v168, -v164, v167, v166
	v_fmac_f32_e32 v167, v168, v165
	v_fma_f32 v164, -v164, v167, v166
	v_div_fmas_f32 v164, v164, v165, v167
	v_div_fixup_f32 v151, v164, v163, v151
	ds_write_b32 v104, v151 offset:22528
	s_waitcnt vmcnt(9)
	v_mul_f32_e32 v163, 0xbfb8aa3b, v152
	v_exp_f32_e32 v163, v163
	s_nop 0
	v_add_f32_e32 v163, 1.0, v163
	v_div_scale_f32 v164, s[0:1], v163, v163, v152
	v_rcp_f32_e32 v165, v164
	v_div_scale_f32 v166, vcc, v152, v163, v152
	v_fma_f32 v167, -v164, v165, 1.0
	v_fmac_f32_e32 v165, v167, v165
	v_mul_f32_e32 v167, v166, v165
	v_fma_f32 v168, -v164, v167, v166
	v_fmac_f32_e32 v167, v168, v165
	v_fma_f32 v164, -v164, v167, v166
	v_div_fmas_f32 v164, v164, v165, v167
	v_div_fixup_f32 v152, v164, v163, v152
	ds_write_b32 v104, v152 offset:23552
	s_waitcnt vmcnt(8)
	v_mul_f32_e32 v163, 0xbfb8aa3b, v153
	v_exp_f32_e32 v163, v163
	s_nop 0
	v_add_f32_e32 v163, 1.0, v163
	v_div_scale_f32 v164, s[0:1], v163, v163, v153
	v_rcp_f32_e32 v165, v164
	v_div_scale_f32 v166, vcc, v153, v163, v153
	v_fma_f32 v167, -v164, v165, 1.0
	v_fmac_f32_e32 v165, v167, v165
	v_mul_f32_e32 v167, v166, v165
	v_fma_f32 v168, -v164, v167, v166
	v_fmac_f32_e32 v167, v168, v165
	v_fma_f32 v164, -v164, v167, v166
	v_div_fmas_f32 v164, v164, v165, v167
	v_div_fixup_f32 v153, v164, v163, v153
	ds_write_b32 v104, v153 offset:24576
	s_waitcnt vmcnt(7)
	v_mul_f32_e32 v163, 0xbfb8aa3b, v154
	v_exp_f32_e32 v163, v163
	s_nop 0
	v_add_f32_e32 v163, 1.0, v163
	v_div_scale_f32 v164, s[0:1], v163, v163, v154
	v_rcp_f32_e32 v165, v164
	v_div_scale_f32 v166, vcc, v154, v163, v154
	v_fma_f32 v167, -v164, v165, 1.0
	v_fmac_f32_e32 v165, v167, v165
	v_mul_f32_e32 v167, v166, v165
	v_fma_f32 v168, -v164, v167, v166
	v_fmac_f32_e32 v167, v168, v165
	v_fma_f32 v164, -v164, v167, v166
	v_div_fmas_f32 v164, v164, v165, v167
	v_div_fixup_f32 v154, v164, v163, v154
	ds_write_b32 v104, v154 offset:25600
	s_waitcnt vmcnt(6)
	v_mul_f32_e32 v163, 0xbfb8aa3b, v155
	v_exp_f32_e32 v163, v163
	s_nop 0
	v_add_f32_e32 v163, 1.0, v163
	v_div_scale_f32 v164, s[0:1], v163, v163, v155
	v_rcp_f32_e32 v165, v164
	v_div_scale_f32 v166, vcc, v155, v163, v155
	v_fma_f32 v167, -v164, v165, 1.0
	v_fmac_f32_e32 v165, v167, v165
	v_mul_f32_e32 v167, v166, v165
	v_fma_f32 v168, -v164, v167, v166
	v_fmac_f32_e32 v167, v168, v165
	v_fma_f32 v164, -v164, v167, v166
	v_div_fmas_f32 v164, v164, v165, v167
	v_div_fixup_f32 v155, v164, v163, v155
	ds_write_b32 v104, v155 offset:26624
	s_waitcnt vmcnt(5)
	v_mul_f32_e32 v163, 0xbfb8aa3b, v156
	v_exp_f32_e32 v163, v163
	s_nop 0
	v_add_f32_e32 v163, 1.0, v163
	v_div_scale_f32 v164, s[0:1], v163, v163, v156
	v_rcp_f32_e32 v165, v164
	v_div_scale_f32 v166, vcc, v156, v163, v156
	v_fma_f32 v167, -v164, v165, 1.0
	v_fmac_f32_e32 v165, v167, v165
	v_mul_f32_e32 v167, v166, v165
	v_fma_f32 v168, -v164, v167, v166
	v_fmac_f32_e32 v167, v168, v165
	v_fma_f32 v164, -v164, v167, v166
	v_div_fmas_f32 v164, v164, v165, v167
	v_div_fixup_f32 v156, v164, v163, v156
	ds_write_b32 v104, v156 offset:27648
	s_waitcnt vmcnt(4)
	v_mul_f32_e32 v163, 0xbfb8aa3b, v157
	v_exp_f32_e32 v163, v163
	s_nop 0
	v_add_f32_e32 v163, 1.0, v163
	v_div_scale_f32 v164, s[0:1], v163, v163, v157
	v_rcp_f32_e32 v165, v164
	v_div_scale_f32 v166, vcc, v157, v163, v157
	v_fma_f32 v167, -v164, v165, 1.0
	v_fmac_f32_e32 v165, v167, v165
	v_mul_f32_e32 v167, v166, v165
	v_fma_f32 v168, -v164, v167, v166
	v_fmac_f32_e32 v167, v168, v165
	v_fma_f32 v164, -v164, v167, v166
	v_div_fmas_f32 v164, v164, v165, v167
	v_div_fixup_f32 v157, v164, v163, v157
	ds_write_b32 v104, v157 offset:28672
	s_waitcnt vmcnt(3)
	v_mul_f32_e32 v163, 0xbfb8aa3b, v158
	v_exp_f32_e32 v163, v163
	s_nop 0
	v_add_f32_e32 v163, 1.0, v163
	v_div_scale_f32 v164, s[0:1], v163, v163, v158
	v_rcp_f32_e32 v165, v164
	v_div_scale_f32 v166, vcc, v158, v163, v158
	v_fma_f32 v167, -v164, v165, 1.0
	v_fmac_f32_e32 v165, v167, v165
	v_mul_f32_e32 v167, v166, v165
	v_fma_f32 v168, -v164, v167, v166
	v_fmac_f32_e32 v167, v168, v165
	v_fma_f32 v164, -v164, v167, v166
	v_div_fmas_f32 v164, v164, v165, v167
	v_div_fixup_f32 v158, v164, v163, v158
	ds_write_b32 v104, v158 offset:29696
	s_waitcnt vmcnt(2)
	v_mul_f32_e32 v163, 0xbfb8aa3b, v159
	v_exp_f32_e32 v163, v163
	s_nop 0
	v_add_f32_e32 v163, 1.0, v163
	v_div_scale_f32 v164, s[0:1], v163, v163, v159
	v_rcp_f32_e32 v165, v164
	v_div_scale_f32 v166, vcc, v159, v163, v159
	v_fma_f32 v167, -v164, v165, 1.0
	v_fmac_f32_e32 v165, v167, v165
	v_mul_f32_e32 v167, v166, v165
	v_fma_f32 v168, -v164, v167, v166
	v_fmac_f32_e32 v167, v168, v165
	v_fma_f32 v164, -v164, v167, v166
	v_div_fmas_f32 v164, v164, v165, v167
	v_div_fixup_f32 v159, v164, v163, v159
	ds_write_b32 v104, v159 offset:30720
	s_waitcnt vmcnt(1)
	v_mul_f32_e32 v163, 0xbfb8aa3b, v160
	v_exp_f32_e32 v163, v163
	s_nop 0
	v_add_f32_e32 v163, 1.0, v163
	v_div_scale_f32 v164, s[0:1], v163, v163, v160
	v_rcp_f32_e32 v165, v164
	v_div_scale_f32 v166, vcc, v160, v163, v160
	v_fma_f32 v167, -v164, v165, 1.0
	v_fmac_f32_e32 v165, v167, v165
	v_mul_f32_e32 v167, v166, v165
	v_fma_f32 v168, -v164, v167, v166
	v_fmac_f32_e32 v167, v168, v165
	v_fma_f32 v164, -v164, v167, v166
	v_div_fmas_f32 v164, v164, v165, v167
	v_div_fixup_f32 v160, v164, v163, v160
	ds_write_b32 v104, v160 offset:31744
	s_waitcnt vmcnt(0)
	v_mul_f32_e32 v163, 0xbfb8aa3b, v161
	v_exp_f32_e32 v163, v163
	s_nop 0
	v_add_f32_e32 v163, 1.0, v163
	v_div_scale_f32 v164, s[0:1], v163, v163, v161
	v_rcp_f32_e32 v165, v164
	v_div_scale_f32 v166, vcc, v161, v163, v161
	v_fma_f32 v167, -v164, v165, 1.0
	v_fmac_f32_e32 v165, v167, v165
	v_mul_f32_e32 v167, v166, v165
	v_fma_f32 v168, -v164, v167, v166
	v_fmac_f32_e32 v167, v168, v165
	v_fma_f32 v164, -v164, v167, v166
	v_div_fmas_f32 v164, v164, v165, v167
	v_div_fixup_f32 v161, v164, v163, v161
	ds_write_b32 v104, v161 offset:32768
	s_mov_b32 s58, 0x9000
